# P2y RWKV prompt item preamble: previous-row loads no longer waited + converted ahead of the 43 token loads (converted behind their first counted wait)
# baseline (speedup 1.0000x reference)
.LBB0_836:
	s_mov_b32 s42, 0
	s_and_b64 vcc, exec, s[2:3]
	s_cbranch_vccz .LBB0_838
	s_mul_i32 s1, s52, 0xe00
	s_mul_hi_i32 s0, s52, 0xe00
	s_add_u32 s1, s56, s1
	s_addc_u32 s2, s57, s0
	s_lshl_b32 s0, s58, 1
	s_add_u32 s0, s1, s0
	s_addc_u32 s1, s2, 0
	global_load_ushort v251, v48, s[0:1]
	global_load_ushort v252, v48, s[0:1] offset:1024
	global_load_ushort v253, v48, s[0:1] offset:2048
	s_branch .LBB0_839
.LBB0_838:
	v_mov_b32_e32 v251, 0
	v_mov_b32_e32 v252, 0
	v_mov_b32_e32 v253, 0
	v_mov_b32_e32 v147, 0
.LBB0_839:
	s_lshl_b32 s52, s58, 1
	s_and_b32 s0, s83, 7
	s_lshl_b32 s43, s0, 8
	s_or_b32 s0, s45, s59
	v_lshl_add_u64 v[140:141], v[52:53], 0, s[52:53]
	s_ashr_i32 s1, s0, 31
	v_mad_i64_i32 v[16:17], s[2:3], s0, v173, v[140:141]
	s_lshl_b64 s[2:3], s[0:1], 9
	v_mov_b32_e32 v20, s58
	global_load_ushort v147, v[16:17], off
	global_load_ushort v157, v[16:17], off offset:1024
	global_load_ushort v174, v[16:17], off offset:2048
	v_or3_b32 v17, s3, 0, 0
	v_or3_b32 v16, s2, v158, v20
	v_lshlrev_b64 v[16:17], 1, v[16:17]
	s_or_b32 s2, s0, 1
	v_lshl_add_u64 v[18:19], s[62:63], 0, v[16:17]
	v_lshl_add_u64 v[16:17], s[90:91], 0, v[16:17]
	s_ashr_i32 s3, s2, 31
	global_load_ushort v175, v[18:19], off
	global_load_ushort v177, v[16:17], off
	v_mad_i64_i32 v[16:17], s[54:55], s2, v173, v[140:141]
	s_lshl_b64 s[2:3], s[2:3], 9
	global_load_ushort v181, v[16:17], off
	global_load_ushort v183, v[16:17], off offset:1024
	global_load_ushort v184, v[16:17], off offset:2048
	v_or3_b32 v17, s3, 0, 0
	v_or3_b32 v16, s2, v158, v20
	v_lshlrev_b64 v[16:17], 1, v[16:17]
	s_or_b32 s2, s0, 2
	v_lshl_add_u64 v[18:19], s[62:63], 0, v[16:17]
	v_lshl_add_u64 v[16:17], s[90:91], 0, v[16:17]
	s_ashr_i32 s3, s2, 31
	global_load_ushort v185, v[18:19], off
	global_load_ushort v186, v[16:17], off
	v_mad_i64_i32 v[16:17], s[54:55], s2, v173, v[140:141]
	s_lshl_b64 s[2:3], s[2:3], 9
	global_load_ushort v187, v[16:17], off
	global_load_ushort v188, v[16:17], off offset:1024
	global_load_ushort v189, v[16:17], off offset:2048
	v_or3_b32 v17, s3, 0, 0
	v_or3_b32 v16, s2, v158, v20
	v_lshlrev_b64 v[16:17], 1, v[16:17]
	s_or_b32 s2, s0, 3
	v_lshl_add_u64 v[18:19], s[62:63], 0, v[16:17]
	v_lshl_add_u64 v[16:17], s[90:91], 0, v[16:17]
	s_ashr_i32 s3, s2, 31
	global_load_ushort v193, v[18:19], off
	global_load_ushort v194, v[16:17], off
	v_mad_i64_i32 v[16:17], s[54:55], s2, v173, v[140:141]
	s_lshl_b64 s[2:3], s[2:3], 9
	s_add_i32 s1, s0, 15
	global_load_ushort v195, v[16:17], off
	global_load_ushort v21, v[16:17], off offset:1024
	global_load_ushort v22, v[16:17], off offset:2048
	v_or3_b32 v16, s2, v158, v20
	s_mul_hi_i32 s2, s1, 0xe00
	s_mulk_i32 s1, 0xe00
	s_add_u32 s1, s56, s1
	v_or3_b32 v17, s3, 0, 0
	s_addc_u32 s3, s57, s2
	v_lshlrev_b64 v[16:17], 1, v[16:17]
	s_add_u32 s2, s1, s52
	v_lshl_add_u64 v[18:19], s[62:63], 0, v[16:17]
	s_addc_u32 s3, s3, 0
	v_lshl_add_u64 v[16:17], s[90:91], 0, v[16:17]
	global_load_ushort v200, v[18:19], off
	global_load_ushort v202, v[16:17], off
	global_load_ushort v23, v48, s[2:3]
	global_load_ushort v24, v48, s[2:3] offset:2048
	global_load_ushort v25, v48, s[2:3] offset:1024
	s_or_b32 s2, s0, 16
	s_ashr_i32 s3, s2, 31
	v_mad_i64_i32 v[16:17], s[54:55], s2, v173, v[140:141]
	s_lshl_b64 s[2:3], s[2:3], 9
	global_load_ushort v190, v[16:17], off
	global_load_ushort v191, v[16:17], off offset:1024
	global_load_ushort v192, v[16:17], off offset:2048
	v_or3_b32 v17, s3, 0, 0
	v_or3_b32 v16, s2, v158, v20
	v_lshlrev_b64 v[16:17], 1, v[16:17]
	s_or_b32 s2, s0, 17
	v_lshl_add_u64 v[18:19], s[62:63], 0, v[16:17]
	v_lshl_add_u64 v[16:17], s[90:91], 0, v[16:17]
	s_ashr_i32 s3, s2, 31
	global_load_ushort v196, v[18:19], off
	global_load_ushort v197, v[16:17], off
	v_mad_i64_i32 v[16:17], s[54:55], s2, v173, v[140:141]
	s_lshl_b64 s[2:3], s[2:3], 9
	global_load_ushort v198, v[16:17], off
	global_load_ushort v199, v[16:17], off offset:1024
	global_load_ushort v201, v[16:17], off offset:2048
	v_or3_b32 v17, s3, 0, 0
	v_or3_b32 v16, s2, v158, v20
	v_lshlrev_b64 v[16:17], 1, v[16:17]
	s_or_b32 s2, s0, 18
	v_lshl_add_u64 v[18:19], s[62:63], 0, v[16:17]
	v_lshl_add_u64 v[16:17], s[90:91], 0, v[16:17]
	s_ashr_i32 s3, s2, 31
	global_load_ushort v205, v[18:19], off
	global_load_ushort v206, v[16:17], off
	v_mad_i64_i32 v[16:17], s[54:55], s2, v173, v[140:141]
	s_lshl_b64 s[2:3], s[2:3], 9
	global_load_ushort v212, v[16:17], off
	global_load_ushort v213, v[16:17], off offset:1024
	global_load_ushort v214, v[16:17], off offset:2048
	v_or3_b32 v17, s3, 0, 0
	v_or3_b32 v16, s2, v158, v20
	v_lshlrev_b64 v[16:17], 1, v[16:17]
	s_or_b32 s0, s0, 19
	v_lshl_add_u64 v[18:19], s[62:63], 0, v[16:17]
	v_lshl_add_u64 v[16:17], s[90:91], 0, v[16:17]
	s_ashr_i32 s1, s0, 31
	global_load_ushort v215, v[18:19], off
	global_load_ushort v216, v[16:17], off
	v_mad_i64_i32 v[16:17], s[2:3], s0, v173, v[140:141]
	s_lshl_b64 s[0:1], s[0:1], 9
	global_load_ushort v217, v[16:17], off
	global_load_ushort v26, v[16:17], off offset:1024
	global_load_ushort v27, v[16:17], off offset:2048
	v_or3_b32 v17, s1, 0, 0
	v_or3_b32 v16, s0, v158, v20
	v_lshlrev_b64 v[16:17], 1, v[16:17]
	v_lshl_add_u64 v[18:19], s[62:63], 0, v[16:17]
	v_lshl_add_u64 v[16:17], s[90:91], 0, v[16:17]
	global_load_ushort v218, v[18:19], off
	global_load_ushort v219, v[16:17], off
	v_readlane_b32 s0, v249, 62
	s_waitcnt vmcnt(39)
	v_lshlrev_b32_e32 v146, 16, v251
	v_lshlrev_b32_e32 v145, 16, v252
	v_lshlrev_b32_e32 v144, 16, v253
	v_lshlrev_b32_e32 v16, 16, v175
	s_waitcnt vmcnt(34)
	v_lshlrev_b32_e32 v17, 16, v185
	v_add_u32_e32 v203, s0, v65
	v_readlane_b32 s0, v248, 9
	ds_write_b32 v203, v16 offset:13824
	v_add_f32_e32 v16, 0, v16
	v_add_u32_e32 v204, s0, v65
	v_readlane_b32 s0, v248, 10
	ds_write_b32 v204, v17 offset:13824
	v_add_f32_e32 v16, v16, v17
	v_add_u32_e32 v207, s0, v65
	s_waitcnt vmcnt(29)
	v_lshlrev_b32_e32 v17, 16, v193
	ds_write_b32 v207, v17 offset:13824
	v_add_f32_e32 v16, v16, v17
	v_readlane_b32 s0, v248, 11
	v_lshl_add_u64 v[142:143], v[60:61], 0, s[52:53]
	s_add_i32 s2, s44, s43
	v_add_u32_e32 v211, s0, v65
	s_waitcnt vmcnt(25)
	v_perm_b32 v221, v21, v22, s96
	s_waitcnt vmcnt(24)
	v_lshlrev_b32_e32 v17, 16, v200
	s_waitcnt vmcnt(22)
	v_lshlrev_b32_e32 v223, 16, v23
	s_waitcnt vmcnt(20)
	v_lshlrev_b32_e32 v49, 16, v25
	v_lshlrev_b32_e32 v56, 16, v24
	v_add_f32_e32 v16, v16, v17
	ds_write_b32 v211, v17 offset:13824
	ds_write_b32 v67, v16 offset:22016
	s_waitcnt vmcnt(2)
	v_perm_b32 v220, v26, v27, s96
	s_branch .LBB0_841
